# down-projection and PLE-gate GEMM K-loops: ordinary units run an unguarded copy of the loop; the wave-half guards stay only in the shared tail-unit loop
# speedup vs baseline: 1.0118x; 1.0118x over previous
.LBB0_1903:
	s_add_u32 s69, s36, 0x100
	v_mov_b32_e32 v0, 0
	s_addc_u32 s72, s37, 0
	s_mov_b32 s73, -2
	s_waitcnt lgkmcnt(0)
	v_mov_b32_e32 v1, v0
	v_mov_b32_e32 v2, v0
	v_mov_b32_e32 v3, v0
	v_mov_b32_e32 v4, v0
	v_mov_b32_e32 v5, v0
	v_mov_b32_e32 v6, v0
	v_mov_b32_e32 v7, v0
	v_mov_b32_e32 v16, v0
	v_mov_b32_e32 v17, v0
	v_mov_b32_e32 v18, v0
	v_mov_b32_e32 v19, v0
	v_mov_b32_e32 v20, v0
	v_mov_b32_e32 v21, v0
	v_mov_b32_e32 v22, v0
	v_mov_b32_e32 v23, v0
	s_waitcnt vmcnt(0)
	v_mov_b32_e32 v32, v0
	v_mov_b32_e32 v33, v0
	v_mov_b32_e32 v34, v0
	v_mov_b32_e32 v35, v0
	v_mov_b32_e32 v36, v0
	v_mov_b32_e32 v37, v0
	v_mov_b32_e32 v38, v0
	v_mov_b32_e32 v39, v0
	v_mov_b32_e32 v48, v0
	v_mov_b32_e32 v49, v0
	v_mov_b32_e32 v50, v0
	v_mov_b32_e32 v51, v0
	v_mov_b32_e32 v52, v0
	v_mov_b32_e32 v53, v0
	v_mov_b32_e32 v54, v0
	v_mov_b32_e32 v55, v0
	v_mov_b32_e32 v8, v0
	v_mov_b32_e32 v9, v0
	v_mov_b32_e32 v10, v0
	v_mov_b32_e32 v11, v0
	v_mov_b32_e32 v12, v0
	v_mov_b32_e32 v13, v0
	v_mov_b32_e32 v14, v0
	v_mov_b32_e32 v15, v0
	v_mov_b32_e32 v24, v0
	v_mov_b32_e32 v25, v0
	v_mov_b32_e32 v26, v0
	v_mov_b32_e32 v27, v0
	v_mov_b32_e32 v28, v0
	v_mov_b32_e32 v29, v0
	v_mov_b32_e32 v30, v0
	v_mov_b32_e32 v31, v0
	v_mov_b32_e32 v40, v0
	v_mov_b32_e32 v41, v0
	v_mov_b32_e32 v42, v0
	v_mov_b32_e32 v43, v0
	v_mov_b32_e32 v44, v0
	v_mov_b32_e32 v45, v0
	v_mov_b32_e32 v46, v0
	v_mov_b32_e32 v47, v0
	v_mov_b32_e32 v56, v0
	v_mov_b32_e32 v57, v0
	v_mov_b32_e32 v58, v0
	v_mov_b32_e32 v59, v0
	v_mov_b32_e32 v60, v0
	v_mov_b32_e32 v61, v0
	v_mov_b32_e32 v62, v0
	v_mov_b32_e32 v63, v0
	v_mov_b32_e32 v64, v0
	v_mov_b32_e32 v65, v0
	v_mov_b32_e32 v66, v0
	v_mov_b32_e32 v67, v0
	v_mov_b32_e32 v68, v0
	v_mov_b32_e32 v69, v0
	v_mov_b32_e32 v70, v0
	v_mov_b32_e32 v71, v0
	v_mov_b32_e32 v80, v0
	v_mov_b32_e32 v81, v0
	v_mov_b32_e32 v82, v0
	v_mov_b32_e32 v83, v0
	v_mov_b32_e32 v84, v0
	v_mov_b32_e32 v85, v0
	v_mov_b32_e32 v86, v0
	v_mov_b32_e32 v87, v0
	v_mov_b32_e32 v96, v0
	v_mov_b32_e32 v97, v0
	v_mov_b32_e32 v98, v0
	v_mov_b32_e32 v99, v0
	v_mov_b32_e32 v100, v0
	v_mov_b32_e32 v101, v0
	v_mov_b32_e32 v102, v0
	v_mov_b32_e32 v103, v0
	v_mov_b32_e32 v112, v0
	v_mov_b32_e32 v113, v0
	v_mov_b32_e32 v114, v0
	v_mov_b32_e32 v115, v0
	v_mov_b32_e32 v116, v0
	v_mov_b32_e32 v117, v0
	v_mov_b32_e32 v118, v0
	v_mov_b32_e32 v119, v0
	v_mov_b32_e32 v72, v0
	v_mov_b32_e32 v73, v0
	v_mov_b32_e32 v74, v0
	v_mov_b32_e32 v75, v0
	v_mov_b32_e32 v76, v0
	v_mov_b32_e32 v77, v0
	v_mov_b32_e32 v78, v0
	v_mov_b32_e32 v79, v0
	v_mov_b32_e32 v88, v0
	v_mov_b32_e32 v89, v0
	v_mov_b32_e32 v90, v0
	v_mov_b32_e32 v91, v0
	v_mov_b32_e32 v92, v0
	v_mov_b32_e32 v93, v0
	v_mov_b32_e32 v94, v0
	v_mov_b32_e32 v95, v0
	v_mov_b32_e32 v104, v0
	v_mov_b32_e32 v105, v0
	v_mov_b32_e32 v106, v0
	v_mov_b32_e32 v107, v0
	v_mov_b32_e32 v108, v0
	v_mov_b32_e32 v109, v0
	v_mov_b32_e32 v110, v0
	v_mov_b32_e32 v111, v0
	v_mov_b32_e32 v120, v0
	v_mov_b32_e32 v121, v0
	v_mov_b32_e32 v122, v0
	v_mov_b32_e32 v123, v0
	v_mov_b32_e32 v124, v0
	v_mov_b32_e32 v125, v0
	v_mov_b32_e32 v126, v0
	v_mov_b32_e32 v127, v0
	s_cmp_eq_u32 s49, 2
	s_cbranch_scc1 .LBB0_1904
.Lng_p5:
	ds_read_b128 v[146:149], v157
	ds_read_b128 v[150:153], v157 offset:1024
	ds_read_b128 v[162:165], v157 offset:2048
	ds_read_b128 v[166:169], v157 offset:3072
	ds_read_b128 v[170:173], v158
	ds_read_b128 v[176:179], v158 offset:1024
	ds_read_b128 v[180:183], v158 offset:2048
	ds_read_b128 v[184:187], v158 offset:3072
	s_add_u32 s36, s34, 0x100
	s_addc_u32 s37, s35, 0
	s_cmp_eq_u32 s73, 40
	s_cselect_b32 s41, s13, s37
	s_cselect_b32 s40, s12, s36
	s_cselect_b32 s39, s31, s72
	s_cselect_b32 s38, s30, s69
	v_lshl_add_u64 v[220:221], s[34:35], 0, v[138:139]
	s_add_i32 m0, s45, 0xc000
	ds_read_b128 v[188:191], v159
	ds_read_b128 v[192:195], v159 offset:1024
	ds_read_b128 v[196:199], v159 offset:2048
	ds_read_b128 v[200:203], v159 offset:3072
	ds_read_b128 v[204:207], v159 offset:4096
	ds_read_b128 v[208:211], v159 offset:5120
	ds_read_b128 v[212:215], v159 offset:6144
	ds_read_b128 v[216:219], v159 offset:7168
	global_load_lds_dwordx4 v[220:221], off
	v_lshl_add_u64 v[220:221], s[34:35], 0, v[140:141]
	s_add_i32 m0, s45, 0xe000
	s_nop 0
	global_load_lds_dwordx4 v[220:221], off
	s_waitcnt vmcnt(8)
	s_waitcnt lgkmcnt(0)
	s_barrier
	s_setprio 1
	s_waitcnt lgkmcnt(0)
	v_mfma_f32_16x16x32_bf16 v[124:127], v[146:149], v[188:191], v[124:127]
	v_mfma_f32_16x16x32_bf16 v[120:123], v[162:165], v[188:191], v[120:123]
	v_mfma_f32_16x16x32_bf16 v[108:111], v[146:149], v[196:199], v[108:111]
	v_mfma_f32_16x16x32_bf16 v[104:107], v[162:165], v[196:199], v[104:107]
	v_mfma_f32_16x16x32_bf16 v[92:95], v[146:149], v[204:207], v[92:95]
	v_mfma_f32_16x16x32_bf16 v[88:91], v[162:165], v[204:207], v[88:91]
	v_mfma_f32_16x16x32_bf16 v[76:79], v[146:149], v[212:215], v[76:79]
	v_mfma_f32_16x16x32_bf16 v[72:75], v[162:165], v[212:215], v[72:75]
	v_mfma_f32_16x16x32_bf16 v[124:127], v[150:153], v[192:195], v[124:127]
	v_mfma_f32_16x16x32_bf16 v[120:123], v[166:169], v[192:195], v[120:123]
	v_mfma_f32_16x16x32_bf16 v[108:111], v[150:153], v[200:203], v[108:111]
	v_mfma_f32_16x16x32_bf16 v[104:107], v[166:169], v[200:203], v[104:107]
	v_mfma_f32_16x16x32_bf16 v[92:95], v[150:153], v[208:211], v[92:95]
	v_mfma_f32_16x16x32_bf16 v[88:91], v[166:169], v[208:211], v[88:91]
	v_mfma_f32_16x16x32_bf16 v[76:79], v[150:153], v[216:219], v[76:79]
	v_mfma_f32_16x16x32_bf16 v[72:75], v[166:169], v[216:219], v[72:75]
	s_setprio 0
	s_setprio 1
	v_mfma_f32_16x16x32_bf16 v[116:119], v[170:173], v[188:191], v[116:119]
	v_mfma_f32_16x16x32_bf16 v[112:115], v[180:183], v[188:191], v[112:115]
	v_mfma_f32_16x16x32_bf16 v[100:103], v[170:173], v[196:199], v[100:103]
	v_mfma_f32_16x16x32_bf16 v[96:99], v[180:183], v[196:199], v[96:99]
	v_mfma_f32_16x16x32_bf16 v[84:87], v[170:173], v[204:207], v[84:87]
	v_mfma_f32_16x16x32_bf16 v[80:83], v[180:183], v[204:207], v[80:83]
	v_mfma_f32_16x16x32_bf16 v[68:71], v[170:173], v[212:215], v[68:71]
	v_mfma_f32_16x16x32_bf16 v[64:67], v[180:183], v[212:215], v[64:67]
	v_mfma_f32_16x16x32_bf16 v[116:119], v[176:179], v[192:195], v[116:119]
	v_mfma_f32_16x16x32_bf16 v[112:115], v[184:187], v[192:195], v[112:115]
	v_mfma_f32_16x16x32_bf16 v[100:103], v[176:179], v[200:203], v[100:103]
	v_mfma_f32_16x16x32_bf16 v[96:99], v[184:187], v[200:203], v[96:99]
	v_mfma_f32_16x16x32_bf16 v[84:87], v[176:179], v[208:211], v[84:87]
	v_mfma_f32_16x16x32_bf16 v[80:83], v[184:187], v[208:211], v[80:83]
	v_mfma_f32_16x16x32_bf16 v[68:71], v[176:179], v[216:219], v[68:71]
	v_mfma_f32_16x16x32_bf16 v[64:67], v[184:187], v[216:219], v[64:67]
	s_setprio 0
	s_barrier
	s_add_i32 s34, s55, s44
	v_lshl_add_u64 v[220:221], s[38:39], 0, v[130:131]
	s_mov_b32 m0, s34
	ds_read_b128 v[188:191], v159 offset:16384
	ds_read_b128 v[192:195], v159 offset:17408
	ds_read_b128 v[196:199], v159 offset:18432
	ds_read_b128 v[200:203], v159 offset:19456
	ds_read_b128 v[204:207], v159 offset:20480
	ds_read_b128 v[208:211], v159 offset:21504
	ds_read_b128 v[212:215], v159 offset:22528
	ds_read_b128 v[216:219], v159 offset:23552
	global_load_lds_dwordx4 v[220:221], off
	s_add_i32 m0, s34, 0x2000
	s_add_u32 s34, s38, 0xb0000
	v_lshl_add_u64 v[222:223], s[38:39], 0, v[134:135]
	s_addc_u32 s35, s39, 0
	s_add_i32 s74, s56, s44
	global_load_lds_dwordx4 v[222:223], off
	v_lshl_add_u64 v[224:225], s[34:35], 0, v[130:131]
	s_mov_b32 m0, s74
	v_lshl_add_u64 v[226:227], s[40:41], 0, v[132:133]
	global_load_lds_dwordx4 v[224:225], off
	v_lshl_add_u64 v[224:225], s[34:35], 0, v[134:135]
	s_add_i32 m0, s74, 0x2000
	s_nop 0
	global_load_lds_dwordx4 v[224:225], off
	v_lshl_add_u64 v[224:225], s[40:41], 0, v[128:129]
	s_mov_b32 m0, s45
	s_nop 0
	global_load_lds_dwordx4 v[224:225], off
	s_mov_b32 m0, s46
	s_nop 0
	global_load_lds_dwordx4 v[226:227], off
	s_waitcnt vmcnt(8)
	s_waitcnt lgkmcnt(0)
	s_barrier
	s_setprio 1
	s_waitcnt lgkmcnt(0)
	v_mfma_f32_16x16x32_bf16 v[60:63], v[146:149], v[188:191], v[60:63]
	v_mfma_f32_16x16x32_bf16 v[56:59], v[162:165], v[188:191], v[56:59]
	v_mfma_f32_16x16x32_bf16 v[44:47], v[146:149], v[196:199], v[44:47]
	v_mfma_f32_16x16x32_bf16 v[40:43], v[162:165], v[196:199], v[40:43]
	v_mfma_f32_16x16x32_bf16 v[28:31], v[146:149], v[204:207], v[28:31]
	v_mfma_f32_16x16x32_bf16 v[24:27], v[162:165], v[204:207], v[24:27]
	v_mfma_f32_16x16x32_bf16 v[12:15], v[146:149], v[212:215], v[12:15]
	v_mfma_f32_16x16x32_bf16 v[8:11], v[162:165], v[212:215], v[8:11]
	v_mfma_f32_16x16x32_bf16 v[60:63], v[150:153], v[192:195], v[60:63]
	v_mfma_f32_16x16x32_bf16 v[56:59], v[166:169], v[192:195], v[56:59]
	v_mfma_f32_16x16x32_bf16 v[44:47], v[150:153], v[200:203], v[44:47]
	v_mfma_f32_16x16x32_bf16 v[40:43], v[166:169], v[200:203], v[40:43]
	v_mfma_f32_16x16x32_bf16 v[28:31], v[150:153], v[208:211], v[28:31]
	v_mfma_f32_16x16x32_bf16 v[24:27], v[166:169], v[208:211], v[24:27]
	v_mfma_f32_16x16x32_bf16 v[12:15], v[150:153], v[216:219], v[12:15]
	v_mfma_f32_16x16x32_bf16 v[8:11], v[166:169], v[216:219], v[8:11]
	s_setprio 0
	s_setprio 1
	v_mfma_f32_16x16x32_bf16 v[52:55], v[170:173], v[188:191], v[52:55]
	v_mfma_f32_16x16x32_bf16 v[48:51], v[180:183], v[188:191], v[48:51]
	v_mfma_f32_16x16x32_bf16 v[36:39], v[170:173], v[196:199], v[36:39]
	v_mfma_f32_16x16x32_bf16 v[32:35], v[180:183], v[196:199], v[32:35]
	v_mfma_f32_16x16x32_bf16 v[20:23], v[170:173], v[204:207], v[20:23]
	v_mfma_f32_16x16x32_bf16 v[16:19], v[180:183], v[204:207], v[16:19]
	v_mfma_f32_16x16x32_bf16 v[4:7], v[170:173], v[212:215], v[4:7]
	v_mfma_f32_16x16x32_bf16 v[0:3], v[180:183], v[212:215], v[0:3]
	v_mfma_f32_16x16x32_bf16 v[52:55], v[176:179], v[192:195], v[52:55]
	v_mfma_f32_16x16x32_bf16 v[48:51], v[184:187], v[192:195], v[48:51]
	v_mfma_f32_16x16x32_bf16 v[36:39], v[176:179], v[200:203], v[36:39]
	v_mfma_f32_16x16x32_bf16 v[32:35], v[184:187], v[200:203], v[32:35]
	v_mfma_f32_16x16x32_bf16 v[20:23], v[176:179], v[208:211], v[20:23]
	v_mfma_f32_16x16x32_bf16 v[16:19], v[184:187], v[208:211], v[16:19]
	v_mfma_f32_16x16x32_bf16 v[4:7], v[176:179], v[216:219], v[4:7]
	v_mfma_f32_16x16x32_bf16 v[0:3], v[184:187], v[216:219], v[0:3]
	s_setprio 0
	s_barrier
	s_add_i32 s74, 0, 0x18000
	v_add_u32_e32 v136, s74, v155
	s_add_i32 s75, 0, 0x1c000
	ds_read_b128 v[146:149], v136
	ds_read_b128 v[150:153], v136 offset:1024
	ds_read_b128 v[162:165], v136 offset:2048
	ds_read_b128 v[166:169], v136 offset:3072
	v_add_u32_e32 v136, s75, v155
	ds_read_b128 v[170:173], v136
	ds_read_b128 v[176:179], v136 offset:1024
	ds_read_b128 v[180:183], v136 offset:2048
	ds_read_b128 v[184:187], v136 offset:3072
	s_add_u32 s34, s40, 0xb0000
	s_addc_u32 s35, s41, 0
	s_mov_b32 m0, s47
	v_lshl_add_u64 v[228:229], s[34:35], 0, v[128:129]
	ds_read_b128 v[188:191], v159 offset:32768
	ds_read_b128 v[192:195], v159 offset:33792
	ds_read_b128 v[196:199], v159 offset:34816
	ds_read_b128 v[200:203], v159 offset:35840
	ds_read_b128 v[204:207], v159 offset:36864
	ds_read_b128 v[208:211], v159 offset:37888
	ds_read_b128 v[212:215], v159 offset:38912
	ds_read_b128 v[216:219], v159 offset:39936
	global_load_lds_dwordx4 v[228:229], off
	v_lshl_add_u64 v[228:229], s[34:35], 0, v[132:133]
	s_mov_b32 m0, s48
	s_nop 0
	global_load_lds_dwordx4 v[228:229], off
	s_waitcnt vmcnt(8)
	s_waitcnt lgkmcnt(0)
	s_barrier
	s_setprio 1
	s_waitcnt lgkmcnt(0)
	v_mfma_f32_16x16x32_bf16 v[124:127], v[146:149], v[188:191], v[124:127]
	v_mfma_f32_16x16x32_bf16 v[120:123], v[162:165], v[188:191], v[120:123]
	v_mfma_f32_16x16x32_bf16 v[108:111], v[146:149], v[196:199], v[108:111]
	v_mfma_f32_16x16x32_bf16 v[104:107], v[162:165], v[196:199], v[104:107]
	v_mfma_f32_16x16x32_bf16 v[92:95], v[146:149], v[204:207], v[92:95]
	v_mfma_f32_16x16x32_bf16 v[88:91], v[162:165], v[204:207], v[88:91]
	v_mfma_f32_16x16x32_bf16 v[76:79], v[146:149], v[212:215], v[76:79]
	v_mfma_f32_16x16x32_bf16 v[72:75], v[162:165], v[212:215], v[72:75]
	v_mfma_f32_16x16x32_bf16 v[124:127], v[150:153], v[192:195], v[124:127]
	v_mfma_f32_16x16x32_bf16 v[120:123], v[166:169], v[192:195], v[120:123]
	v_mfma_f32_16x16x32_bf16 v[108:111], v[150:153], v[200:203], v[108:111]
	v_mfma_f32_16x16x32_bf16 v[104:107], v[166:169], v[200:203], v[104:107]
	v_mfma_f32_16x16x32_bf16 v[92:95], v[150:153], v[208:211], v[92:95]
	v_mfma_f32_16x16x32_bf16 v[88:91], v[166:169], v[208:211], v[88:91]
	v_mfma_f32_16x16x32_bf16 v[76:79], v[150:153], v[216:219], v[76:79]
	v_mfma_f32_16x16x32_bf16 v[72:75], v[166:169], v[216:219], v[72:75]
	s_setprio 0
	s_setprio 1
	v_mfma_f32_16x16x32_bf16 v[116:119], v[170:173], v[188:191], v[116:119]
	v_mfma_f32_16x16x32_bf16 v[112:115], v[180:183], v[188:191], v[112:115]
	v_mfma_f32_16x16x32_bf16 v[100:103], v[170:173], v[196:199], v[100:103]
	v_mfma_f32_16x16x32_bf16 v[96:99], v[180:183], v[196:199], v[96:99]
	v_mfma_f32_16x16x32_bf16 v[84:87], v[170:173], v[204:207], v[84:87]
	v_mfma_f32_16x16x32_bf16 v[80:83], v[180:183], v[204:207], v[80:83]
	v_mfma_f32_16x16x32_bf16 v[68:71], v[170:173], v[212:215], v[68:71]
	v_mfma_f32_16x16x32_bf16 v[64:67], v[180:183], v[212:215], v[64:67]
	v_mfma_f32_16x16x32_bf16 v[116:119], v[176:179], v[192:195], v[116:119]
	v_mfma_f32_16x16x32_bf16 v[112:115], v[184:187], v[192:195], v[112:115]
	v_mfma_f32_16x16x32_bf16 v[100:103], v[176:179], v[200:203], v[100:103]
	v_mfma_f32_16x16x32_bf16 v[96:99], v[184:187], v[200:203], v[96:99]
	v_mfma_f32_16x16x32_bf16 v[84:87], v[176:179], v[208:211], v[84:87]
	v_mfma_f32_16x16x32_bf16 v[80:83], v[184:187], v[208:211], v[80:83]
	v_mfma_f32_16x16x32_bf16 v[68:71], v[176:179], v[216:219], v[68:71]
	v_mfma_f32_16x16x32_bf16 v[64:67], v[184:187], v[216:219], v[64:67]
	s_setprio 0
	s_barrier
	s_add_i32 s34, s74, s44
	v_lshl_add_u64 v[220:221], v[220:221], 0, s[26:27]
	s_mov_b32 m0, s34
	ds_read_b128 v[188:191], v159 offset:49152
	ds_read_b128 v[192:195], v159 offset:50176
	ds_read_b128 v[196:199], v159 offset:51200
	ds_read_b128 v[200:203], v159 offset:52224
	ds_read_b128 v[204:207], v159 offset:53248
	ds_read_b128 v[208:211], v159 offset:54272
	ds_read_b128 v[212:215], v159 offset:55296
	ds_read_b128 v[216:219], v159 offset:56320
	global_load_lds_dwordx4 v[220:221], off
	s_add_i32 m0, s34, 0x2000
	s_add_u32 s34, s38, 0xb0080
	v_lshl_add_u64 v[220:221], v[222:223], 0, s[26:27]
	s_addc_u32 s35, s39, 0
	s_add_i32 s38, s75, s44
	global_load_lds_dwordx4 v[220:221], off
	v_lshl_add_u64 v[220:221], s[34:35], 0, v[130:131]
	s_mov_b32 m0, s38
	s_nop 0
	global_load_lds_dwordx4 v[220:221], off
	v_lshl_add_u64 v[220:221], s[34:35], 0, v[134:135]
	s_add_i32 m0, s38, 0x2000
	s_nop 0
	global_load_lds_dwordx4 v[220:221], off
	v_lshl_add_u64 v[220:221], v[224:225], 0, s[26:27]
	s_mov_b32 m0, s50
	s_nop 0
	global_load_lds_dwordx4 v[220:221], off
	v_lshl_add_u64 v[220:221], v[226:227], 0, s[26:27]
	s_mov_b32 m0, s51
	s_nop 0
	global_load_lds_dwordx4 v[220:221], off
	s_waitcnt vmcnt(8)
	s_waitcnt lgkmcnt(0)
	s_barrier
	s_setprio 1
	s_waitcnt lgkmcnt(0)
	v_mfma_f32_16x16x32_bf16 v[60:63], v[146:149], v[188:191], v[60:63]
	v_mfma_f32_16x16x32_bf16 v[56:59], v[162:165], v[188:191], v[56:59]
	v_mfma_f32_16x16x32_bf16 v[44:47], v[146:149], v[196:199], v[44:47]
	v_mfma_f32_16x16x32_bf16 v[40:43], v[162:165], v[196:199], v[40:43]
	v_mfma_f32_16x16x32_bf16 v[28:31], v[146:149], v[204:207], v[28:31]
	v_mfma_f32_16x16x32_bf16 v[24:27], v[162:165], v[204:207], v[24:27]
	v_mfma_f32_16x16x32_bf16 v[12:15], v[146:149], v[212:215], v[12:15]
	v_mfma_f32_16x16x32_bf16 v[8:11], v[162:165], v[212:215], v[8:11]
	v_mfma_f32_16x16x32_bf16 v[60:63], v[150:153], v[192:195], v[60:63]
	v_mfma_f32_16x16x32_bf16 v[56:59], v[166:169], v[192:195], v[56:59]
	v_mfma_f32_16x16x32_bf16 v[44:47], v[150:153], v[200:203], v[44:47]
	v_mfma_f32_16x16x32_bf16 v[40:43], v[166:169], v[200:203], v[40:43]
	v_mfma_f32_16x16x32_bf16 v[28:31], v[150:153], v[208:211], v[28:31]
	v_mfma_f32_16x16x32_bf16 v[24:27], v[166:169], v[208:211], v[24:27]
	v_mfma_f32_16x16x32_bf16 v[12:15], v[150:153], v[216:219], v[12:15]
	v_mfma_f32_16x16x32_bf16 v[8:11], v[166:169], v[216:219], v[8:11]
	s_setprio 0
	s_setprio 1
	v_mfma_f32_16x16x32_bf16 v[52:55], v[170:173], v[188:191], v[52:55]
	v_mfma_f32_16x16x32_bf16 v[48:51], v[180:183], v[188:191], v[48:51]
	v_mfma_f32_16x16x32_bf16 v[36:39], v[170:173], v[196:199], v[36:39]
	v_mfma_f32_16x16x32_bf16 v[32:35], v[180:183], v[196:199], v[32:35]
	v_mfma_f32_16x16x32_bf16 v[20:23], v[170:173], v[204:207], v[20:23]
	v_mfma_f32_16x16x32_bf16 v[16:19], v[180:183], v[204:207], v[16:19]
	v_mfma_f32_16x16x32_bf16 v[4:7], v[170:173], v[212:215], v[4:7]
	v_mfma_f32_16x16x32_bf16 v[0:3], v[180:183], v[212:215], v[0:3]
	v_mfma_f32_16x16x32_bf16 v[52:55], v[176:179], v[192:195], v[52:55]
	v_mfma_f32_16x16x32_bf16 v[48:51], v[184:187], v[192:195], v[48:51]
	v_mfma_f32_16x16x32_bf16 v[36:39], v[176:179], v[200:203], v[36:39]
	v_mfma_f32_16x16x32_bf16 v[32:35], v[184:187], v[200:203], v[32:35]
	v_mfma_f32_16x16x32_bf16 v[20:23], v[176:179], v[208:211], v[20:23]
	v_mfma_f32_16x16x32_bf16 v[16:19], v[184:187], v[208:211], v[16:19]
	v_mfma_f32_16x16x32_bf16 v[4:7], v[176:179], v[216:219], v[4:7]
	v_mfma_f32_16x16x32_bf16 v[0:3], v[184:187], v[216:219], v[0:3]
	s_setprio 0
	s_barrier
	s_add_i32 s73, s73, 2
	s_add_u32 s69, s69, 0x100
	s_addc_u32 s72, s72, 0
	s_cmp_gt_u32 s73, 41
	s_mov_b64 s[34:35], s[36:37]
	s_cbranch_scc0 .Lng_p5
	s_branch .Lng_p5_done

.Lng_p5_done:
	s_and_b64 vcc, exec, s[28:29]
	s_cbranch_vccz .LBB0_1907
	s_barrier

.LBB0_2039:
	s_ashr_i32 s27, s26, 31
	s_lshl_b64 s[28:29], s[26:27], 19
	s_add_u32 s28, s3, s28
	s_addc_u32 s29, s4, s29
	s_and_b64 s[30:31], s[8:9], exec
	s_cselect_b32 s27, s29, s39
	s_cselect_b32 s35, s28, s38
	s_ashr_i32 s25, s24, 31
	s_lshl_b64 s[30:31], s[24:25], 19
	s_add_u32 s30, s5, s30
	s_addc_u32 s31, s44, s31
	s_and_b64 s[42:43], s[8:9], exec
	s_cselect_b32 s25, s31, s41
	s_cselect_b32 s58, s30, s40
	s_add_u32 s38, s38, 0x40080
	s_addc_u32 s39, s39, 0
	s_add_u32 s59, s40, 0x100
	v_mov_b32_e32 v0, 0
	s_addc_u32 s60, s41, 0
	s_mov_b32 s61, -2
	s_waitcnt lgkmcnt(0)
	v_mov_b32_e32 v1, v0
	v_mov_b32_e32 v2, v0
	v_mov_b32_e32 v3, v0
	v_mov_b32_e32 v4, v0
	v_mov_b32_e32 v5, v0
	v_mov_b32_e32 v6, v0
	v_mov_b32_e32 v7, v0
	v_mov_b32_e32 v16, v0
	v_mov_b32_e32 v17, v0
	v_mov_b32_e32 v18, v0
	v_mov_b32_e32 v19, v0
	v_mov_b32_e32 v20, v0
	v_mov_b32_e32 v21, v0
	v_mov_b32_e32 v22, v0
	v_mov_b32_e32 v23, v0
	v_mov_b32_e32 v32, v0
	v_mov_b32_e32 v33, v0
	v_mov_b32_e32 v34, v0
	v_mov_b32_e32 v35, v0
	v_mov_b32_e32 v36, v0
	v_mov_b32_e32 v37, v0
	v_mov_b32_e32 v38, v0
	v_mov_b32_e32 v39, v0
	v_mov_b32_e32 v48, v0
	v_mov_b32_e32 v49, v0
	v_mov_b32_e32 v50, v0
	v_mov_b32_e32 v51, v0
	v_mov_b32_e32 v52, v0
	v_mov_b32_e32 v53, v0
	v_mov_b32_e32 v54, v0
	v_mov_b32_e32 v55, v0
	v_mov_b32_e32 v8, v0
	v_mov_b32_e32 v9, v0
	v_mov_b32_e32 v10, v0
	v_mov_b32_e32 v11, v0
	v_mov_b32_e32 v12, v0
	v_mov_b32_e32 v13, v0
	v_mov_b32_e32 v14, v0
	v_mov_b32_e32 v15, v0
	v_mov_b32_e32 v24, v0
	v_mov_b32_e32 v25, v0
	v_mov_b32_e32 v26, v0
	v_mov_b32_e32 v27, v0
	v_mov_b32_e32 v28, v0
	v_mov_b32_e32 v29, v0
	v_mov_b32_e32 v30, v0
	v_mov_b32_e32 v31, v0
	v_mov_b32_e32 v40, v0
	v_mov_b32_e32 v41, v0
	v_mov_b32_e32 v42, v0
	v_mov_b32_e32 v43, v0
	v_mov_b32_e32 v44, v0
	v_mov_b32_e32 v45, v0
	v_mov_b32_e32 v46, v0
	v_mov_b32_e32 v47, v0
	v_mov_b32_e32 v56, v0
	v_mov_b32_e32 v57, v0
	v_mov_b32_e32 v58, v0
	v_mov_b32_e32 v59, v0
	v_mov_b32_e32 v60, v0
	v_mov_b32_e32 v61, v0
	v_mov_b32_e32 v62, v0
	v_mov_b32_e32 v63, v0
	v_mov_b32_e32 v64, v0
	v_mov_b32_e32 v65, v0
	v_mov_b32_e32 v66, v0
	v_mov_b32_e32 v67, v0
	v_mov_b32_e32 v68, v0
	v_mov_b32_e32 v69, v0
	v_mov_b32_e32 v70, v0
	v_mov_b32_e32 v71, v0
	v_mov_b32_e32 v80, v0
	v_mov_b32_e32 v81, v0
	v_mov_b32_e32 v82, v0
	v_mov_b32_e32 v83, v0
	v_mov_b32_e32 v84, v0
	v_mov_b32_e32 v85, v0
	v_mov_b32_e32 v86, v0
	v_mov_b32_e32 v87, v0
	v_mov_b32_e32 v96, v0
	v_mov_b32_e32 v97, v0
	v_mov_b32_e32 v98, v0
	v_mov_b32_e32 v99, v0
	v_mov_b32_e32 v100, v0
	v_mov_b32_e32 v101, v0
	v_mov_b32_e32 v102, v0
	v_mov_b32_e32 v103, v0
	v_mov_b32_e32 v112, v0
	v_mov_b32_e32 v113, v0
	v_mov_b32_e32 v114, v0
	v_mov_b32_e32 v115, v0
	v_mov_b32_e32 v116, v0
	v_mov_b32_e32 v117, v0
	v_mov_b32_e32 v118, v0
	v_mov_b32_e32 v119, v0
	v_mov_b32_e32 v72, v0
	v_mov_b32_e32 v73, v0
	v_mov_b32_e32 v74, v0
	v_mov_b32_e32 v75, v0
	v_mov_b32_e32 v76, v0
	v_mov_b32_e32 v77, v0
	v_mov_b32_e32 v78, v0
	v_mov_b32_e32 v79, v0
	v_mov_b32_e32 v88, v0
	v_mov_b32_e32 v89, v0
	v_mov_b32_e32 v90, v0
	v_mov_b32_e32 v91, v0
	v_mov_b32_e32 v92, v0
	v_mov_b32_e32 v93, v0
	v_mov_b32_e32 v94, v0
	v_mov_b32_e32 v95, v0
	v_mov_b32_e32 v104, v0
	v_mov_b32_e32 v105, v0
	v_mov_b32_e32 v106, v0
	v_mov_b32_e32 v107, v0
	v_mov_b32_e32 v108, v0
	v_mov_b32_e32 v109, v0
	v_mov_b32_e32 v110, v0
	v_mov_b32_e32 v111, v0
	v_mov_b32_e32 v120, v0
	v_mov_b32_e32 v121, v0
	v_mov_b32_e32 v122, v0
	v_mov_b32_e32 v123, v0
	v_mov_b32_e32 v124, v0
	v_mov_b32_e32 v125, v0
	v_mov_b32_e32 v126, v0
	v_mov_b32_e32 v127, v0
	s_cmp_eq_u32 s49, 2
	s_cbranch_scc1 .LBB0_2040
.Lng_p6:
	ds_read_b128 v[144:147], v155
	ds_read_b128 v[148:151], v155 offset:1024
	ds_read_b128 v[160:163], v155 offset:2048
	ds_read_b128 v[164:167], v155 offset:3072
	ds_read_b128 v[168:171], v156
	ds_read_b128 v[176:179], v156 offset:1024
	ds_read_b128 v[180:183], v156 offset:2048
	ds_read_b128 v[184:187], v156 offset:3072
	s_add_u32 s40, s38, 0xfffc0080
	s_addc_u32 s41, s39, -1
	s_cmp_eq_u32 s61, 12
	s_cselect_b32 s43, s27, s41
	s_cselect_b32 s42, s35, s40
	s_cselect_b32 s41, s25, s60
	s_cselect_b32 s40, s58, s59
	v_lshl_add_u64 v[172:173], s[38:39], 0, v[136:137]
	s_add_i32 m0, s37, 0xc000
	ds_read_b128 v[188:191], v157
	ds_read_b128 v[192:195], v157 offset:1024
	ds_read_b128 v[196:199], v157 offset:2048
	ds_read_b128 v[200:203], v157 offset:3072
	ds_read_b128 v[204:207], v157 offset:4096
	ds_read_b128 v[208:211], v157 offset:5120
	ds_read_b128 v[212:215], v157 offset:6144
	ds_read_b128 v[216:219], v157 offset:7168
	global_load_lds_dwordx4 v[172:173], off
	v_lshl_add_u64 v[172:173], s[38:39], 0, v[138:139]
	s_add_i32 m0, s37, 0xe000
	s_nop 0
	global_load_lds_dwordx4 v[172:173], off
	s_waitcnt vmcnt(8)
	s_waitcnt lgkmcnt(0)
	s_barrier
	s_setprio 1
	s_waitcnt lgkmcnt(0)
	v_mfma_f32_16x16x32_bf16 v[124:127], v[144:147], v[188:191], v[124:127]
	v_mfma_f32_16x16x32_bf16 v[120:123], v[160:163], v[188:191], v[120:123]
	v_mfma_f32_16x16x32_bf16 v[108:111], v[144:147], v[196:199], v[108:111]
	v_mfma_f32_16x16x32_bf16 v[104:107], v[160:163], v[196:199], v[104:107]
	v_mfma_f32_16x16x32_bf16 v[92:95], v[144:147], v[204:207], v[92:95]
	v_mfma_f32_16x16x32_bf16 v[88:91], v[160:163], v[204:207], v[88:91]
	v_mfma_f32_16x16x32_bf16 v[76:79], v[144:147], v[212:215], v[76:79]
	v_mfma_f32_16x16x32_bf16 v[72:75], v[160:163], v[212:215], v[72:75]
	v_mfma_f32_16x16x32_bf16 v[124:127], v[148:151], v[192:195], v[124:127]
	v_mfma_f32_16x16x32_bf16 v[120:123], v[164:167], v[192:195], v[120:123]
	v_mfma_f32_16x16x32_bf16 v[108:111], v[148:151], v[200:203], v[108:111]
	v_mfma_f32_16x16x32_bf16 v[104:107], v[164:167], v[200:203], v[104:107]
	v_mfma_f32_16x16x32_bf16 v[92:95], v[148:151], v[208:211], v[92:95]
	v_mfma_f32_16x16x32_bf16 v[88:91], v[164:167], v[208:211], v[88:91]
	v_mfma_f32_16x16x32_bf16 v[76:79], v[148:151], v[216:219], v[76:79]
	v_mfma_f32_16x16x32_bf16 v[72:75], v[164:167], v[216:219], v[72:75]
	s_setprio 0
	s_setprio 1
	v_mfma_f32_16x16x32_bf16 v[116:119], v[168:171], v[188:191], v[116:119]
	v_mfma_f32_16x16x32_bf16 v[112:115], v[180:183], v[188:191], v[112:115]
	v_mfma_f32_16x16x32_bf16 v[100:103], v[168:171], v[196:199], v[100:103]
	v_mfma_f32_16x16x32_bf16 v[96:99], v[180:183], v[196:199], v[96:99]
	v_mfma_f32_16x16x32_bf16 v[84:87], v[168:171], v[204:207], v[84:87]
	v_mfma_f32_16x16x32_bf16 v[80:83], v[180:183], v[204:207], v[80:83]
	v_mfma_f32_16x16x32_bf16 v[68:71], v[168:171], v[212:215], v[68:71]
	v_mfma_f32_16x16x32_bf16 v[64:67], v[180:183], v[212:215], v[64:67]
	v_mfma_f32_16x16x32_bf16 v[116:119], v[176:179], v[192:195], v[116:119]
	v_mfma_f32_16x16x32_bf16 v[112:115], v[184:187], v[192:195], v[112:115]
	v_mfma_f32_16x16x32_bf16 v[100:103], v[176:179], v[200:203], v[100:103]
	v_mfma_f32_16x16x32_bf16 v[96:99], v[184:187], v[200:203], v[96:99]
	v_mfma_f32_16x16x32_bf16 v[84:87], v[176:179], v[208:211], v[84:87]
	v_mfma_f32_16x16x32_bf16 v[80:83], v[184:187], v[208:211], v[80:83]
	v_mfma_f32_16x16x32_bf16 v[68:71], v[176:179], v[216:219], v[68:71]
	v_mfma_f32_16x16x32_bf16 v[64:67], v[184:187], v[216:219], v[64:67]
	s_setprio 0
	s_barrier
	s_add_i32 s62, s55, s45
	v_lshl_add_u64 v[172:173], s[40:41], 0, v[130:131]
	s_mov_b32 m0, s62
	ds_read_b128 v[188:191], v157 offset:16384
	ds_read_b128 v[192:195], v157 offset:17408
	ds_read_b128 v[196:199], v157 offset:18432
	ds_read_b128 v[200:203], v157 offset:19456
	ds_read_b128 v[204:207], v157 offset:20480
	ds_read_b128 v[208:211], v157 offset:21504
	ds_read_b128 v[212:215], v157 offset:22528
	ds_read_b128 v[216:219], v157 offset:23552
	global_load_lds_dwordx4 v[172:173], off
	s_add_i32 m0, s62, 0x2000
	s_add_u32 s62, s40, 0x40000
	v_lshl_add_u64 v[220:221], s[40:41], 0, v[134:135]
	s_addc_u32 s63, s41, 0
	s_add_i32 s65, s56, s45
	global_load_lds_dwordx4 v[220:221], off
	v_lshl_add_u64 v[222:223], s[62:63], 0, v[130:131]
	s_mov_b32 m0, s65
	v_lshl_add_u64 v[224:225], s[42:43], 0, v[132:133]
	global_load_lds_dwordx4 v[222:223], off
	v_lshl_add_u64 v[222:223], s[62:63], 0, v[134:135]
	s_add_i32 m0, s65, 0x2000
	s_nop 0
	global_load_lds_dwordx4 v[222:223], off
	v_lshl_add_u64 v[222:223], s[42:43], 0, v[128:129]
	s_mov_b32 m0, s37
	s_nop 0
	global_load_lds_dwordx4 v[222:223], off
	s_mov_b32 m0, s46
	s_nop 0
	global_load_lds_dwordx4 v[224:225], off
	s_waitcnt vmcnt(8)
	s_waitcnt lgkmcnt(0)
	s_barrier
	s_setprio 1
	s_waitcnt lgkmcnt(0)
	v_mfma_f32_16x16x32_bf16 v[60:63], v[144:147], v[188:191], v[60:63]
	v_mfma_f32_16x16x32_bf16 v[56:59], v[160:163], v[188:191], v[56:59]
	v_mfma_f32_16x16x32_bf16 v[44:47], v[144:147], v[196:199], v[44:47]
	v_mfma_f32_16x16x32_bf16 v[40:43], v[160:163], v[196:199], v[40:43]
	v_mfma_f32_16x16x32_bf16 v[28:31], v[144:147], v[204:207], v[28:31]
	v_mfma_f32_16x16x32_bf16 v[24:27], v[160:163], v[204:207], v[24:27]
	v_mfma_f32_16x16x32_bf16 v[12:15], v[144:147], v[212:215], v[12:15]
	v_mfma_f32_16x16x32_bf16 v[8:11], v[160:163], v[212:215], v[8:11]
	v_mfma_f32_16x16x32_bf16 v[60:63], v[148:151], v[192:195], v[60:63]
	v_mfma_f32_16x16x32_bf16 v[56:59], v[164:167], v[192:195], v[56:59]
	v_mfma_f32_16x16x32_bf16 v[44:47], v[148:151], v[200:203], v[44:47]
	v_mfma_f32_16x16x32_bf16 v[40:43], v[164:167], v[200:203], v[40:43]
	v_mfma_f32_16x16x32_bf16 v[28:31], v[148:151], v[208:211], v[28:31]
	v_mfma_f32_16x16x32_bf16 v[24:27], v[164:167], v[208:211], v[24:27]
	v_mfma_f32_16x16x32_bf16 v[12:15], v[148:151], v[216:219], v[12:15]
	v_mfma_f32_16x16x32_bf16 v[8:11], v[164:167], v[216:219], v[8:11]
	s_setprio 0
	s_setprio 1
	v_mfma_f32_16x16x32_bf16 v[52:55], v[168:171], v[188:191], v[52:55]
	v_mfma_f32_16x16x32_bf16 v[48:51], v[180:183], v[188:191], v[48:51]
	v_mfma_f32_16x16x32_bf16 v[36:39], v[168:171], v[196:199], v[36:39]
	v_mfma_f32_16x16x32_bf16 v[32:35], v[180:183], v[196:199], v[32:35]
	v_mfma_f32_16x16x32_bf16 v[20:23], v[168:171], v[204:207], v[20:23]
	v_mfma_f32_16x16x32_bf16 v[16:19], v[180:183], v[204:207], v[16:19]
	v_mfma_f32_16x16x32_bf16 v[4:7], v[168:171], v[212:215], v[4:7]
	v_mfma_f32_16x16x32_bf16 v[0:3], v[180:183], v[212:215], v[0:3]
	v_mfma_f32_16x16x32_bf16 v[52:55], v[176:179], v[192:195], v[52:55]
	v_mfma_f32_16x16x32_bf16 v[48:51], v[184:187], v[192:195], v[48:51]
	v_mfma_f32_16x16x32_bf16 v[36:39], v[176:179], v[200:203], v[36:39]
	v_mfma_f32_16x16x32_bf16 v[32:35], v[184:187], v[200:203], v[32:35]
	v_mfma_f32_16x16x32_bf16 v[20:23], v[176:179], v[208:211], v[20:23]
	v_mfma_f32_16x16x32_bf16 v[16:19], v[184:187], v[208:211], v[16:19]
	v_mfma_f32_16x16x32_bf16 v[4:7], v[176:179], v[216:219], v[4:7]
	v_mfma_f32_16x16x32_bf16 v[0:3], v[184:187], v[216:219], v[0:3]
	s_setprio 0
	s_barrier
	s_add_i32 s62, 0, 0x18000
	s_add_i32 s63, 0, 0x1c000
	v_add_u32_e32 v164, s62, v153
	v_add_u32_e32 v175, s63, v153
	ds_read_b128 v[144:147], v164
	ds_read_b128 v[148:151], v164 offset:1024
	ds_read_b128 v[160:163], v164 offset:2048
	ds_read_b128 v[164:167], v164 offset:3072
	ds_read_b128 v[168:171], v175
	ds_read_b128 v[176:179], v175 offset:1024
	ds_read_b128 v[180:183], v175 offset:2048
	ds_read_b128 v[184:187], v175 offset:3072
	s_add_u32 s42, s42, 0x40000
	s_addc_u32 s43, s43, 0
	s_mov_b32 m0, s47
	v_lshl_add_u64 v[226:227], s[42:43], 0, v[128:129]
	ds_read_b128 v[188:191], v157 offset:32768
	ds_read_b128 v[192:195], v157 offset:33792
	ds_read_b128 v[196:199], v157 offset:34816
	ds_read_b128 v[200:203], v157 offset:35840
	ds_read_b128 v[204:207], v157 offset:36864
	ds_read_b128 v[208:211], v157 offset:37888
	ds_read_b128 v[212:215], v157 offset:38912
	ds_read_b128 v[216:219], v157 offset:39936
	global_load_lds_dwordx4 v[226:227], off
	v_lshl_add_u64 v[226:227], s[42:43], 0, v[132:133]
	s_mov_b32 m0, s48
	s_nop 0
	global_load_lds_dwordx4 v[226:227], off
	s_waitcnt vmcnt(8)
	s_waitcnt lgkmcnt(0)
	s_barrier
	s_setprio 1
	s_waitcnt lgkmcnt(0)
	v_mfma_f32_16x16x32_bf16 v[124:127], v[144:147], v[188:191], v[124:127]
	v_mfma_f32_16x16x32_bf16 v[120:123], v[160:163], v[188:191], v[120:123]
	v_mfma_f32_16x16x32_bf16 v[108:111], v[144:147], v[196:199], v[108:111]
	v_mfma_f32_16x16x32_bf16 v[104:107], v[160:163], v[196:199], v[104:107]
	v_mfma_f32_16x16x32_bf16 v[92:95], v[144:147], v[204:207], v[92:95]
	v_mfma_f32_16x16x32_bf16 v[88:91], v[160:163], v[204:207], v[88:91]
	v_mfma_f32_16x16x32_bf16 v[76:79], v[144:147], v[212:215], v[76:79]
	v_mfma_f32_16x16x32_bf16 v[72:75], v[160:163], v[212:215], v[72:75]
	v_mfma_f32_16x16x32_bf16 v[124:127], v[148:151], v[192:195], v[124:127]
	v_mfma_f32_16x16x32_bf16 v[120:123], v[164:167], v[192:195], v[120:123]
	v_mfma_f32_16x16x32_bf16 v[108:111], v[148:151], v[200:203], v[108:111]
	v_mfma_f32_16x16x32_bf16 v[104:107], v[164:167], v[200:203], v[104:107]
	v_mfma_f32_16x16x32_bf16 v[92:95], v[148:151], v[208:211], v[92:95]
	v_mfma_f32_16x16x32_bf16 v[88:91], v[164:167], v[208:211], v[88:91]
	v_mfma_f32_16x16x32_bf16 v[76:79], v[148:151], v[216:219], v[76:79]
	v_mfma_f32_16x16x32_bf16 v[72:75], v[164:167], v[216:219], v[72:75]
	s_setprio 0
	s_setprio 1
	v_mfma_f32_16x16x32_bf16 v[116:119], v[168:171], v[188:191], v[116:119]
	v_mfma_f32_16x16x32_bf16 v[112:115], v[180:183], v[188:191], v[112:115]
	v_mfma_f32_16x16x32_bf16 v[100:103], v[168:171], v[196:199], v[100:103]
	v_mfma_f32_16x16x32_bf16 v[96:99], v[180:183], v[196:199], v[96:99]
	v_mfma_f32_16x16x32_bf16 v[84:87], v[168:171], v[204:207], v[84:87]
	v_mfma_f32_16x16x32_bf16 v[80:83], v[180:183], v[204:207], v[80:83]
	v_mfma_f32_16x16x32_bf16 v[68:71], v[168:171], v[212:215], v[68:71]
	v_mfma_f32_16x16x32_bf16 v[64:67], v[180:183], v[212:215], v[64:67]
	v_mfma_f32_16x16x32_bf16 v[116:119], v[176:179], v[192:195], v[116:119]
	v_mfma_f32_16x16x32_bf16 v[112:115], v[184:187], v[192:195], v[112:115]
	v_mfma_f32_16x16x32_bf16 v[100:103], v[176:179], v[200:203], v[100:103]
	v_mfma_f32_16x16x32_bf16 v[96:99], v[184:187], v[200:203], v[96:99]
	v_mfma_f32_16x16x32_bf16 v[84:87], v[176:179], v[208:211], v[84:87]
	v_mfma_f32_16x16x32_bf16 v[80:83], v[184:187], v[208:211], v[80:83]
	v_mfma_f32_16x16x32_bf16 v[68:71], v[176:179], v[216:219], v[68:71]
	v_mfma_f32_16x16x32_bf16 v[64:67], v[184:187], v[216:219], v[64:67]
	s_setprio 0
	s_barrier
	s_add_i32 s42, s62, s45
	v_lshl_add_u64 v[172:173], v[172:173], 0, s[20:21]
	s_mov_b32 m0, s42
	ds_read_b128 v[188:191], v157 offset:49152
	ds_read_b128 v[192:195], v157 offset:50176
	ds_read_b128 v[196:199], v157 offset:51200
	ds_read_b128 v[200:203], v157 offset:52224
	ds_read_b128 v[204:207], v157 offset:53248
	ds_read_b128 v[208:211], v157 offset:54272
	ds_read_b128 v[212:215], v157 offset:55296
	ds_read_b128 v[216:219], v157 offset:56320
	global_load_lds_dwordx4 v[172:173], off
	s_add_i32 m0, s42, 0x2000
	s_add_u32 s40, s40, 0x40080
	v_lshl_add_u64 v[172:173], v[220:221], 0, s[20:21]
	s_addc_u32 s41, s41, 0
	s_add_i32 s42, s63, s45
	global_load_lds_dwordx4 v[172:173], off
	v_lshl_add_u64 v[172:173], s[40:41], 0, v[130:131]
	s_mov_b32 m0, s42
	s_nop 0
	global_load_lds_dwordx4 v[172:173], off
	v_lshl_add_u64 v[172:173], s[40:41], 0, v[134:135]
	s_add_i32 m0, s42, 0x2000
	s_nop 0
	global_load_lds_dwordx4 v[172:173], off
	v_lshl_add_u64 v[172:173], v[222:223], 0, s[20:21]
	s_mov_b32 m0, s50
	s_nop 0
	global_load_lds_dwordx4 v[172:173], off
	v_lshl_add_u64 v[172:173], v[224:225], 0, s[20:21]
	s_mov_b32 m0, s51
	s_nop 0
	global_load_lds_dwordx4 v[172:173], off
	s_waitcnt vmcnt(8)
	s_waitcnt lgkmcnt(0)
	s_barrier
	s_setprio 1
	s_waitcnt lgkmcnt(0)
	v_mfma_f32_16x16x32_bf16 v[60:63], v[144:147], v[188:191], v[60:63]
	v_mfma_f32_16x16x32_bf16 v[56:59], v[160:163], v[188:191], v[56:59]
	v_mfma_f32_16x16x32_bf16 v[44:47], v[144:147], v[196:199], v[44:47]
	v_mfma_f32_16x16x32_bf16 v[40:43], v[160:163], v[196:199], v[40:43]
	v_mfma_f32_16x16x32_bf16 v[28:31], v[144:147], v[204:207], v[28:31]
	v_mfma_f32_16x16x32_bf16 v[24:27], v[160:163], v[204:207], v[24:27]
	v_mfma_f32_16x16x32_bf16 v[12:15], v[144:147], v[212:215], v[12:15]
	v_mfma_f32_16x16x32_bf16 v[8:11], v[160:163], v[212:215], v[8:11]
	v_mfma_f32_16x16x32_bf16 v[60:63], v[148:151], v[192:195], v[60:63]
	v_mfma_f32_16x16x32_bf16 v[56:59], v[164:167], v[192:195], v[56:59]
	v_mfma_f32_16x16x32_bf16 v[44:47], v[148:151], v[200:203], v[44:47]
	v_mfma_f32_16x16x32_bf16 v[40:43], v[164:167], v[200:203], v[40:43]
	v_mfma_f32_16x16x32_bf16 v[28:31], v[148:151], v[208:211], v[28:31]
	v_mfma_f32_16x16x32_bf16 v[24:27], v[164:167], v[208:211], v[24:27]
	v_mfma_f32_16x16x32_bf16 v[12:15], v[148:151], v[216:219], v[12:15]
	v_mfma_f32_16x16x32_bf16 v[8:11], v[164:167], v[216:219], v[8:11]
	s_setprio 0
	s_setprio 1
	v_mfma_f32_16x16x32_bf16 v[52:55], v[168:171], v[188:191], v[52:55]
	v_mfma_f32_16x16x32_bf16 v[48:51], v[180:183], v[188:191], v[48:51]
	v_mfma_f32_16x16x32_bf16 v[36:39], v[168:171], v[196:199], v[36:39]
	v_mfma_f32_16x16x32_bf16 v[32:35], v[180:183], v[196:199], v[32:35]
	v_mfma_f32_16x16x32_bf16 v[20:23], v[168:171], v[204:207], v[20:23]
	v_mfma_f32_16x16x32_bf16 v[16:19], v[180:183], v[204:207], v[16:19]
	v_mfma_f32_16x16x32_bf16 v[4:7], v[168:171], v[212:215], v[4:7]
	v_mfma_f32_16x16x32_bf16 v[0:3], v[180:183], v[212:215], v[0:3]
	v_mfma_f32_16x16x32_bf16 v[52:55], v[176:179], v[192:195], v[52:55]
	v_mfma_f32_16x16x32_bf16 v[48:51], v[184:187], v[192:195], v[48:51]
	v_mfma_f32_16x16x32_bf16 v[36:39], v[176:179], v[200:203], v[36:39]
	v_mfma_f32_16x16x32_bf16 v[32:35], v[184:187], v[200:203], v[32:35]
	v_mfma_f32_16x16x32_bf16 v[20:23], v[176:179], v[208:211], v[20:23]
	v_mfma_f32_16x16x32_bf16 v[16:19], v[184:187], v[208:211], v[16:19]
	v_mfma_f32_16x16x32_bf16 v[4:7], v[176:179], v[216:219], v[4:7]
	v_mfma_f32_16x16x32_bf16 v[0:3], v[184:187], v[216:219], v[0:3]
	s_setprio 0
	s_barrier
	s_add_i32 s61, s61, 2
	s_add_u32 s38, s38, 0x100
	s_addc_u32 s39, s39, 0
	s_add_u32 s59, s59, 0x100
	s_addc_u32 s60, s60, 0
	s_cmp_gt_u32 s61, 13
	s_cbranch_scc0 .Lng_p6
	s_branch .Lng_p6_done

.Lng_p6_done:
	s_and_b64 vcc, exec, s[22:23]
	s_cbranch_vccz .LBB0_2043
	s_barrier
